# v17 + P0 modvec: when the grid is 256, unit index permuted so that each XCD takes 32 adjacent column units (shared boundary cache lines meet in one L2)
# baseline (speedup 1.0000x reference)
; __device__ __forceinline__ void p0_modvec(const Params& p, LAS unsigned char* lds, int tid, int lane, int wave) {
;     ...
;     for (int i = tid; i < 9 * 2048; i += 512) { const float v = i < 8 * 2048 ? c[i] : cc[i - 8 * 2048]; svT[(i & 2047) * 12 + (i >> 11)] = v / (1.0f + __expf(-v)); }
.LBB0_12:
	v_lshlrev_b32_e32 v6, 2, v0
	v_mul_u32_u24_e32 v7, 48, v0
	v_add_u32_e32 v8, 0x12000, v7
	global_load_dword v16, v6, s[14:15]
	global_load_dword v17, v6, s[14:15] offset:2048
	s_add_u32 s6, s14, 0x1000
	s_addc_u32 s7, s15, 0
	global_load_dword v18, v6, s[6:7]
	global_load_dword v19, v6, s[6:7] offset:2048
	s_add_u32 s6, s14, 0x2000
	s_addc_u32 s7, s15, 0
	global_load_dword v20, v6, s[6:7]
	global_load_dword v21, v6, s[6:7] offset:2048
	s_add_u32 s6, s14, 0x3000
	s_addc_u32 s7, s15, 0
	global_load_dword v22, v6, s[6:7]
	global_load_dword v23, v6, s[6:7] offset:2048
	s_add_u32 s6, s14, 0x4000
	s_addc_u32 s7, s15, 0
	global_load_dword v24, v6, s[6:7]
	global_load_dword v25, v6, s[6:7] offset:2048
	s_add_u32 s6, s14, 0x5000
	s_addc_u32 s7, s15, 0
	global_load_dword v26, v6, s[6:7]
	global_load_dword v27, v6, s[6:7] offset:2048
	s_add_u32 s6, s14, 0x6000
	s_addc_u32 s7, s15, 0
	global_load_dword v28, v6, s[6:7]
	global_load_dword v29, v6, s[6:7] offset:2048
	s_add_u32 s6, s14, 0x7000
	s_addc_u32 s7, s15, 0
	global_load_dword v30, v6, s[6:7]
	global_load_dword v31, v6, s[6:7] offset:2048
	s_add_u32 s6, s14, 0x8000
	s_addc_u32 s7, s15, 0
	global_load_dword v32, v6, s[6:7]
	global_load_dword v33, v6, s[6:7] offset:2048
	s_add_u32 s6, s14, 0x9000
	s_addc_u32 s7, s15, 0
	global_load_dword v34, v6, s[6:7]
	global_load_dword v35, v6, s[6:7] offset:2048
	s_add_u32 s6, s14, 0xa000
	s_addc_u32 s7, s15, 0
	global_load_dword v36, v6, s[6:7]
	global_load_dword v37, v6, s[6:7] offset:2048
	s_add_u32 s6, s14, 0xb000
	s_addc_u32 s7, s15, 0
	global_load_dword v38, v6, s[6:7]
	global_load_dword v39, v6, s[6:7] offset:2048
	s_add_u32 s6, s14, 0xc000
	s_addc_u32 s7, s15, 0
	global_load_dword v40, v6, s[6:7]
	global_load_dword v41, v6, s[6:7] offset:2048
	s_add_u32 s6, s14, 0xd000
	s_addc_u32 s7, s15, 0
	global_load_dword v42, v6, s[6:7]
	global_load_dword v43, v6, s[6:7] offset:2048
	s_add_u32 s6, s14, 0xe000
	s_addc_u32 s7, s15, 0
	global_load_dword v44, v6, s[6:7]
	global_load_dword v45, v6, s[6:7] offset:2048
	s_add_u32 s6, s14, 0xf000
	s_addc_u32 s7, s15, 0
	global_load_dword v46, v6, s[6:7]
	global_load_dword v47, v6, s[6:7] offset:2048
	global_load_dword v48, v6, s[18:19]
	global_load_dword v49, v6, s[18:19] offset:2048
	s_add_u32 s6, s18, 0x1000
	s_addc_u32 s7, s19, 0
	global_load_dword v50, v6, s[6:7]
	global_load_dword v51, v6, s[6:7] offset:2048
	s_waitcnt vmcnt(35)
	v_mul_f32_e32 v10, 0xbfb8aa3b, v16
	v_exp_f32_e32 v10, v10
	s_nop 0
	v_add_f32_e32 v9, 1.0, v10
	v_div_scale_f32 v10, s[12:13], v9, v9, v16
	v_rcp_f32_e32 v11, v10
	v_div_scale_f32 v12, vcc, v16, v9, v16
	v_fma_f32 v13, -v10, v11, 1.0
	v_fmac_f32_e32 v11, v13, v11
	v_mul_f32_e32 v13, v12, v11
	v_fma_f32 v14, -v10, v13, v12
	v_fmac_f32_e32 v13, v14, v11
	v_fma_f32 v10, -v10, v13, v12
	v_div_fmas_f32 v10, v10, v11, v13
	v_div_fixup_f32 v16, v10, v9, v16
	ds_write_b32 v7, v16 offset:0
	s_waitcnt vmcnt(34)
	v_mul_f32_e32 v10, 0xbfb8aa3b, v17
	v_exp_f32_e32 v10, v10
	s_nop 0
	v_add_f32_e32 v9, 1.0, v10
	v_div_scale_f32 v10, s[12:13], v9, v9, v17
	v_rcp_f32_e32 v11, v10
	v_div_scale_f32 v12, vcc, v17, v9, v17
	v_fma_f32 v13, -v10, v11, 1.0
	v_fmac_f32_e32 v11, v13, v11
	v_mul_f32_e32 v13, v12, v11
	v_fma_f32 v14, -v10, v13, v12
	v_fmac_f32_e32 v13, v14, v11
	v_fma_f32 v10, -v10, v13, v12
	v_div_fmas_f32 v10, v10, v11, v13
	v_div_fixup_f32 v17, v10, v9, v17
	ds_write_b32 v7, v17 offset:24576
	s_waitcnt vmcnt(33)
	v_mul_f32_e32 v10, 0xbfb8aa3b, v18
	v_exp_f32_e32 v10, v10
	s_nop 0
	v_add_f32_e32 v9, 1.0, v10
	v_div_scale_f32 v10, s[12:13], v9, v9, v18
	v_rcp_f32_e32 v11, v10
	v_div_scale_f32 v12, vcc, v18, v9, v18
	v_fma_f32 v13, -v10, v11, 1.0
	v_fmac_f32_e32 v11, v13, v11
	v_mul_f32_e32 v13, v12, v11
	v_fma_f32 v14, -v10, v13, v12
	v_fmac_f32_e32 v13, v14, v11
	v_fma_f32 v10, -v10, v13, v12
	v_div_fmas_f32 v10, v10, v11, v13
	v_div_fixup_f32 v18, v10, v9, v18
	ds_write_b32 v7, v18 offset:49152
	s_waitcnt vmcnt(32)
	v_mul_f32_e32 v10, 0xbfb8aa3b, v19
	v_exp_f32_e32 v10, v10
	s_nop 0
	v_add_f32_e32 v9, 1.0, v10
	v_div_scale_f32 v10, s[12:13], v9, v9, v19
	v_rcp_f32_e32 v11, v10
	v_div_scale_f32 v12, vcc, v19, v9, v19
	v_fma_f32 v13, -v10, v11, 1.0
	v_fmac_f32_e32 v11, v13, v11
	v_mul_f32_e32 v13, v12, v11
	v_fma_f32 v14, -v10, v13, v12
	v_fmac_f32_e32 v13, v14, v11
	v_fma_f32 v10, -v10, v13, v12
	v_div_fmas_f32 v10, v10, v11, v13
	v_div_fixup_f32 v19, v10, v9, v19
	ds_write_b32 v8, v19 offset:0
	s_waitcnt vmcnt(31)
	v_mul_f32_e32 v10, 0xbfb8aa3b, v20
	v_exp_f32_e32 v10, v10
	s_nop 0
	v_add_f32_e32 v9, 1.0, v10
	v_div_scale_f32 v10, s[12:13], v9, v9, v20
	v_rcp_f32_e32 v11, v10
	v_div_scale_f32 v12, vcc, v20, v9, v20
	v_fma_f32 v13, -v10, v11, 1.0
	v_fmac_f32_e32 v11, v13, v11
	v_mul_f32_e32 v13, v12, v11
	v_fma_f32 v14, -v10, v13, v12
	v_fmac_f32_e32 v13, v14, v11
	v_fma_f32 v10, -v10, v13, v12
	v_div_fmas_f32 v10, v10, v11, v13
	v_div_fixup_f32 v20, v10, v9, v20
	ds_write_b32 v7, v20 offset:4
	s_waitcnt vmcnt(30)
	v_mul_f32_e32 v10, 0xbfb8aa3b, v21
	v_exp_f32_e32 v10, v10
	s_nop 0
	v_add_f32_e32 v9, 1.0, v10
	v_div_scale_f32 v10, s[12:13], v9, v9, v21
	v_rcp_f32_e32 v11, v10
	v_div_scale_f32 v12, vcc, v21, v9, v21
	v_fma_f32 v13, -v10, v11, 1.0
	v_fmac_f32_e32 v11, v13, v11
	v_mul_f32_e32 v13, v12, v11
	v_fma_f32 v14, -v10, v13, v12
	v_fmac_f32_e32 v13, v14, v11
	v_fma_f32 v10, -v10, v13, v12
	v_div_fmas_f32 v10, v10, v11, v13
	v_div_fixup_f32 v21, v10, v9, v21
	ds_write_b32 v7, v21 offset:24580
	s_waitcnt vmcnt(29)
; __device__ __forceinline__ void p0_modvec(const Params& p, LAS unsigned char* lds, int tid, int lane, int wave) {
;     ...
;     for (int i = tid; i < 9 * 2048; i += 512) { const float v = i < 8 * 2048 ? c[i] : cc[i - 8 * 2048]; svT[(i & 2047) * 12 + (i >> 11)] = v / (1.0f + __expf(-v)); }
	v_mul_f32_e32 v10, 0xbfb8aa3b, v22
	v_exp_f32_e32 v10, v10
	s_nop 0
	v_add_f32_e32 v9, 1.0, v10
	v_div_scale_f32 v10, s[12:13], v9, v9, v22
	v_rcp_f32_e32 v11, v10
	v_div_scale_f32 v12, vcc, v22, v9, v22
	v_fma_f32 v13, -v10, v11, 1.0
	v_fmac_f32_e32 v11, v13, v11
	v_mul_f32_e32 v13, v12, v11
	v_fma_f32 v14, -v10, v13, v12
	v_fmac_f32_e32 v13, v14, v11
	v_fma_f32 v10, -v10, v13, v12
	v_div_fmas_f32 v10, v10, v11, v13
	v_div_fixup_f32 v22, v10, v9, v22
	ds_write_b32 v7, v22 offset:49156
	s_waitcnt vmcnt(28)
	v_mul_f32_e32 v10, 0xbfb8aa3b, v23
	v_exp_f32_e32 v10, v10
	s_nop 0
	v_add_f32_e32 v9, 1.0, v10
	v_div_scale_f32 v10, s[12:13], v9, v9, v23
	v_rcp_f32_e32 v11, v10
	v_div_scale_f32 v12, vcc, v23, v9, v23
	v_fma_f32 v13, -v10, v11, 1.0
	v_fmac_f32_e32 v11, v13, v11
	v_mul_f32_e32 v13, v12, v11
	v_fma_f32 v14, -v10, v13, v12
	v_fmac_f32_e32 v13, v14, v11
	v_fma_f32 v10, -v10, v13, v12
	v_div_fmas_f32 v10, v10, v11, v13
	v_div_fixup_f32 v23, v10, v9, v23
	ds_write_b32 v8, v23 offset:4
	s_waitcnt vmcnt(27)
	v_mul_f32_e32 v10, 0xbfb8aa3b, v24
	v_exp_f32_e32 v10, v10
	s_nop 0
	v_add_f32_e32 v9, 1.0, v10
	v_div_scale_f32 v10, s[12:13], v9, v9, v24
	v_rcp_f32_e32 v11, v10
	v_div_scale_f32 v12, vcc, v24, v9, v24
	v_fma_f32 v13, -v10, v11, 1.0
	v_fmac_f32_e32 v11, v13, v11
	v_mul_f32_e32 v13, v12, v11
	v_fma_f32 v14, -v10, v13, v12
	v_fmac_f32_e32 v13, v14, v11
	v_fma_f32 v10, -v10, v13, v12
	v_div_fmas_f32 v10, v10, v11, v13
	v_div_fixup_f32 v24, v10, v9, v24
	ds_write_b32 v7, v24 offset:8
	s_waitcnt vmcnt(26)
	v_mul_f32_e32 v10, 0xbfb8aa3b, v25
	v_exp_f32_e32 v10, v10
	s_nop 0
	v_add_f32_e32 v9, 1.0, v10
	v_div_scale_f32 v10, s[12:13], v9, v9, v25
	v_rcp_f32_e32 v11, v10
	v_div_scale_f32 v12, vcc, v25, v9, v25
	v_fma_f32 v13, -v10, v11, 1.0
	v_fmac_f32_e32 v11, v13, v11
	v_mul_f32_e32 v13, v12, v11
	v_fma_f32 v14, -v10, v13, v12
	v_fmac_f32_e32 v13, v14, v11
	v_fma_f32 v10, -v10, v13, v12
	v_div_fmas_f32 v10, v10, v11, v13
	v_div_fixup_f32 v25, v10, v9, v25
	ds_write_b32 v7, v25 offset:24584
	s_waitcnt vmcnt(25)
	v_mul_f32_e32 v10, 0xbfb8aa3b, v26
	v_exp_f32_e32 v10, v10
	s_nop 0
	v_add_f32_e32 v9, 1.0, v10
	v_div_scale_f32 v10, s[12:13], v9, v9, v26
	v_rcp_f32_e32 v11, v10
	v_div_scale_f32 v12, vcc, v26, v9, v26
	v_fma_f32 v13, -v10, v11, 1.0
	v_fmac_f32_e32 v11, v13, v11
	v_mul_f32_e32 v13, v12, v11
	v_fma_f32 v14, -v10, v13, v12
	v_fmac_f32_e32 v13, v14, v11
	v_fma_f32 v10, -v10, v13, v12
	v_div_fmas_f32 v10, v10, v11, v13
	v_div_fixup_f32 v26, v10, v9, v26
	ds_write_b32 v7, v26 offset:49160
	s_waitcnt vmcnt(24)
	v_mul_f32_e32 v10, 0xbfb8aa3b, v27
	v_exp_f32_e32 v10, v10
	s_nop 0
	v_add_f32_e32 v9, 1.0, v10
	v_div_scale_f32 v10, s[12:13], v9, v9, v27
	v_rcp_f32_e32 v11, v10
	v_div_scale_f32 v12, vcc, v27, v9, v27
	v_fma_f32 v13, -v10, v11, 1.0
	v_fmac_f32_e32 v11, v13, v11
	v_mul_f32_e32 v13, v12, v11
	v_fma_f32 v14, -v10, v13, v12
	v_fmac_f32_e32 v13, v14, v11
	v_fma_f32 v10, -v10, v13, v12
	v_div_fmas_f32 v10, v10, v11, v13
	v_div_fixup_f32 v27, v10, v9, v27
	ds_write_b32 v8, v27 offset:8
	s_waitcnt vmcnt(23)
	v_mul_f32_e32 v10, 0xbfb8aa3b, v28
	v_exp_f32_e32 v10, v10
	s_nop 0
	v_add_f32_e32 v9, 1.0, v10
	v_div_scale_f32 v10, s[12:13], v9, v9, v28
	v_rcp_f32_e32 v11, v10
	v_div_scale_f32 v12, vcc, v28, v9, v28
	v_fma_f32 v13, -v10, v11, 1.0
	v_fmac_f32_e32 v11, v13, v11
	v_mul_f32_e32 v13, v12, v11
	v_fma_f32 v14, -v10, v13, v12
	v_fmac_f32_e32 v13, v14, v11
	v_fma_f32 v10, -v10, v13, v12
	v_div_fmas_f32 v10, v10, v11, v13
	v_div_fixup_f32 v28, v10, v9, v28
	ds_write_b32 v7, v28 offset:12
	s_waitcnt vmcnt(22)
	v_mul_f32_e32 v10, 0xbfb8aa3b, v29
	v_exp_f32_e32 v10, v10
	s_nop 0
	v_add_f32_e32 v9, 1.0, v10
	v_div_scale_f32 v10, s[12:13], v9, v9, v29
	v_rcp_f32_e32 v11, v10
	v_div_scale_f32 v12, vcc, v29, v9, v29
	v_fma_f32 v13, -v10, v11, 1.0
	v_fmac_f32_e32 v11, v13, v11
	v_mul_f32_e32 v13, v12, v11
	v_fma_f32 v14, -v10, v13, v12
	v_fmac_f32_e32 v13, v14, v11
	v_fma_f32 v10, -v10, v13, v12
	v_div_fmas_f32 v10, v10, v11, v13
	v_div_fixup_f32 v29, v10, v9, v29
	ds_write_b32 v7, v29 offset:24588
	s_waitcnt vmcnt(21)
	v_mul_f32_e32 v10, 0xbfb8aa3b, v30
	v_exp_f32_e32 v10, v10
	s_nop 0
	v_add_f32_e32 v9, 1.0, v10
	v_div_scale_f32 v10, s[12:13], v9, v9, v30
	v_rcp_f32_e32 v11, v10
	v_div_scale_f32 v12, vcc, v30, v9, v30
	v_fma_f32 v13, -v10, v11, 1.0
	v_fmac_f32_e32 v11, v13, v11
	v_mul_f32_e32 v13, v12, v11
	v_fma_f32 v14, -v10, v13, v12
	v_fmac_f32_e32 v13, v14, v11
	v_fma_f32 v10, -v10, v13, v12
	v_div_fmas_f32 v10, v10, v11, v13
	v_div_fixup_f32 v30, v10, v9, v30
	ds_write_b32 v7, v30 offset:49164
	s_waitcnt vmcnt(20)
	v_mul_f32_e32 v10, 0xbfb8aa3b, v31
	v_exp_f32_e32 v10, v10
	s_nop 0
	v_add_f32_e32 v9, 1.0, v10
	v_div_scale_f32 v10, s[12:13], v9, v9, v31
	v_rcp_f32_e32 v11, v10
	v_div_scale_f32 v12, vcc, v31, v9, v31
	v_fma_f32 v13, -v10, v11, 1.0
	v_fmac_f32_e32 v11, v13, v11
	v_mul_f32_e32 v13, v12, v11
	v_fma_f32 v14, -v10, v13, v12
	v_fmac_f32_e32 v13, v14, v11
	v_fma_f32 v10, -v10, v13, v12
	v_div_fmas_f32 v10, v10, v11, v13
	v_div_fixup_f32 v31, v10, v9, v31
	ds_write_b32 v8, v31 offset:12
	s_waitcnt vmcnt(19)
	v_mul_f32_e32 v10, 0xbfb8aa3b, v32
	v_exp_f32_e32 v10, v10
	s_nop 0
	v_add_f32_e32 v9, 1.0, v10
	v_div_scale_f32 v10, s[12:13], v9, v9, v32
	v_rcp_f32_e32 v11, v10
	v_div_scale_f32 v12, vcc, v32, v9, v32
	v_fma_f32 v13, -v10, v11, 1.0
	v_fmac_f32_e32 v11, v13, v11
	v_mul_f32_e32 v13, v12, v11
	v_fma_f32 v14, -v10, v13, v12
	v_fmac_f32_e32 v13, v14, v11
	v_fma_f32 v10, -v10, v13, v12
	v_div_fmas_f32 v10, v10, v11, v13
	v_div_fixup_f32 v32, v10, v9, v32
	ds_write_b32 v7, v32 offset:16
	s_waitcnt vmcnt(18)
; __device__ __forceinline__ void p0_modvec(const Params& p, LAS unsigned char* lds, int tid, int lane, int wave) {
;     ...
;     for (int i = tid; i < 9 * 2048; i += 512) { const float v = i < 8 * 2048 ? c[i] : cc[i - 8 * 2048]; svT[(i & 2047) * 12 + (i >> 11)] = v / (1.0f + __expf(-v)); }
	v_mul_f32_e32 v10, 0xbfb8aa3b, v33
	v_exp_f32_e32 v10, v10
	s_nop 0
	v_add_f32_e32 v9, 1.0, v10
	v_div_scale_f32 v10, s[12:13], v9, v9, v33
	v_rcp_f32_e32 v11, v10
	v_div_scale_f32 v12, vcc, v33, v9, v33
	v_fma_f32 v13, -v10, v11, 1.0
	v_fmac_f32_e32 v11, v13, v11
	v_mul_f32_e32 v13, v12, v11
	v_fma_f32 v14, -v10, v13, v12
	v_fmac_f32_e32 v13, v14, v11
	v_fma_f32 v10, -v10, v13, v12
	v_div_fmas_f32 v10, v10, v11, v13
	v_div_fixup_f32 v33, v10, v9, v33
	ds_write_b32 v7, v33 offset:24592
	s_waitcnt vmcnt(17)
	v_mul_f32_e32 v10, 0xbfb8aa3b, v34
	v_exp_f32_e32 v10, v10
	s_nop 0
	v_add_f32_e32 v9, 1.0, v10
	v_div_scale_f32 v10, s[12:13], v9, v9, v34
	v_rcp_f32_e32 v11, v10
	v_div_scale_f32 v12, vcc, v34, v9, v34
	v_fma_f32 v13, -v10, v11, 1.0
	v_fmac_f32_e32 v11, v13, v11
	v_mul_f32_e32 v13, v12, v11
	v_fma_f32 v14, -v10, v13, v12
	v_fmac_f32_e32 v13, v14, v11
	v_fma_f32 v10, -v10, v13, v12
	v_div_fmas_f32 v10, v10, v11, v13
	v_div_fixup_f32 v34, v10, v9, v34
	ds_write_b32 v7, v34 offset:49168
	s_waitcnt vmcnt(16)
	v_mul_f32_e32 v10, 0xbfb8aa3b, v35
	v_exp_f32_e32 v10, v10
	s_nop 0
	v_add_f32_e32 v9, 1.0, v10
	v_div_scale_f32 v10, s[12:13], v9, v9, v35
	v_rcp_f32_e32 v11, v10
	v_div_scale_f32 v12, vcc, v35, v9, v35
	v_fma_f32 v13, -v10, v11, 1.0
	v_fmac_f32_e32 v11, v13, v11
	v_mul_f32_e32 v13, v12, v11
	v_fma_f32 v14, -v10, v13, v12
	v_fmac_f32_e32 v13, v14, v11
	v_fma_f32 v10, -v10, v13, v12
	v_div_fmas_f32 v10, v10, v11, v13
	v_div_fixup_f32 v35, v10, v9, v35
	ds_write_b32 v8, v35 offset:16
	s_waitcnt vmcnt(15)
	v_mul_f32_e32 v10, 0xbfb8aa3b, v36
	v_exp_f32_e32 v10, v10
	s_nop 0
	v_add_f32_e32 v9, 1.0, v10
	v_div_scale_f32 v10, s[12:13], v9, v9, v36
	v_rcp_f32_e32 v11, v10
	v_div_scale_f32 v12, vcc, v36, v9, v36
	v_fma_f32 v13, -v10, v11, 1.0
	v_fmac_f32_e32 v11, v13, v11
	v_mul_f32_e32 v13, v12, v11
	v_fma_f32 v14, -v10, v13, v12
	v_fmac_f32_e32 v13, v14, v11
	v_fma_f32 v10, -v10, v13, v12
	v_div_fmas_f32 v10, v10, v11, v13
	v_div_fixup_f32 v36, v10, v9, v36
	ds_write_b32 v7, v36 offset:20
	s_waitcnt vmcnt(14)
	v_mul_f32_e32 v10, 0xbfb8aa3b, v37
	v_exp_f32_e32 v10, v10
	s_nop 0
	v_add_f32_e32 v9, 1.0, v10
	v_div_scale_f32 v10, s[12:13], v9, v9, v37
	v_rcp_f32_e32 v11, v10
	v_div_scale_f32 v12, vcc, v37, v9, v37
	v_fma_f32 v13, -v10, v11, 1.0
	v_fmac_f32_e32 v11, v13, v11
	v_mul_f32_e32 v13, v12, v11
	v_fma_f32 v14, -v10, v13, v12
	v_fmac_f32_e32 v13, v14, v11
	v_fma_f32 v10, -v10, v13, v12
	v_div_fmas_f32 v10, v10, v11, v13
	v_div_fixup_f32 v37, v10, v9, v37
	ds_write_b32 v7, v37 offset:24596
	s_waitcnt vmcnt(13)
	v_mul_f32_e32 v10, 0xbfb8aa3b, v38
	v_exp_f32_e32 v10, v10
	s_nop 0
	v_add_f32_e32 v9, 1.0, v10
	v_div_scale_f32 v10, s[12:13], v9, v9, v38
	v_rcp_f32_e32 v11, v10
	v_div_scale_f32 v12, vcc, v38, v9, v38
	v_fma_f32 v13, -v10, v11, 1.0
	v_fmac_f32_e32 v11, v13, v11
	v_mul_f32_e32 v13, v12, v11
	v_fma_f32 v14, -v10, v13, v12
	v_fmac_f32_e32 v13, v14, v11
	v_fma_f32 v10, -v10, v13, v12
	v_div_fmas_f32 v10, v10, v11, v13
	v_div_fixup_f32 v38, v10, v9, v38
	ds_write_b32 v7, v38 offset:49172
	s_waitcnt vmcnt(12)
	v_mul_f32_e32 v10, 0xbfb8aa3b, v39
	v_exp_f32_e32 v10, v10
	s_nop 0
	v_add_f32_e32 v9, 1.0, v10
	v_div_scale_f32 v10, s[12:13], v9, v9, v39
	v_rcp_f32_e32 v11, v10
	v_div_scale_f32 v12, vcc, v39, v9, v39
	v_fma_f32 v13, -v10, v11, 1.0
	v_fmac_f32_e32 v11, v13, v11
	v_mul_f32_e32 v13, v12, v11
	v_fma_f32 v14, -v10, v13, v12
	v_fmac_f32_e32 v13, v14, v11
	v_fma_f32 v10, -v10, v13, v12
	v_div_fmas_f32 v10, v10, v11, v13
	v_div_fixup_f32 v39, v10, v9, v39
	ds_write_b32 v8, v39 offset:20
	s_waitcnt vmcnt(11)
	v_mul_f32_e32 v10, 0xbfb8aa3b, v40
	v_exp_f32_e32 v10, v10
	s_nop 0
	v_add_f32_e32 v9, 1.0, v10
	v_div_scale_f32 v10, s[12:13], v9, v9, v40
	v_rcp_f32_e32 v11, v10
	v_div_scale_f32 v12, vcc, v40, v9, v40
	v_fma_f32 v13, -v10, v11, 1.0
	v_fmac_f32_e32 v11, v13, v11
	v_mul_f32_e32 v13, v12, v11
	v_fma_f32 v14, -v10, v13, v12
	v_fmac_f32_e32 v13, v14, v11
	v_fma_f32 v10, -v10, v13, v12
	v_div_fmas_f32 v10, v10, v11, v13
	v_div_fixup_f32 v40, v10, v9, v40
	ds_write_b32 v7, v40 offset:24
	s_waitcnt vmcnt(10)
	v_mul_f32_e32 v10, 0xbfb8aa3b, v41
	v_exp_f32_e32 v10, v10
	s_nop 0
	v_add_f32_e32 v9, 1.0, v10
	v_div_scale_f32 v10, s[12:13], v9, v9, v41
	v_rcp_f32_e32 v11, v10
	v_div_scale_f32 v12, vcc, v41, v9, v41
	v_fma_f32 v13, -v10, v11, 1.0
	v_fmac_f32_e32 v11, v13, v11
	v_mul_f32_e32 v13, v12, v11
	v_fma_f32 v14, -v10, v13, v12
	v_fmac_f32_e32 v13, v14, v11
	v_fma_f32 v10, -v10, v13, v12
	v_div_fmas_f32 v10, v10, v11, v13
	v_div_fixup_f32 v41, v10, v9, v41
	ds_write_b32 v7, v41 offset:24600
	s_waitcnt vmcnt(9)
	v_mul_f32_e32 v10, 0xbfb8aa3b, v42
	v_exp_f32_e32 v10, v10
	s_nop 0
	v_add_f32_e32 v9, 1.0, v10
	v_div_scale_f32 v10, s[12:13], v9, v9, v42
	v_rcp_f32_e32 v11, v10
	v_div_scale_f32 v12, vcc, v42, v9, v42
	v_fma_f32 v13, -v10, v11, 1.0
	v_fmac_f32_e32 v11, v13, v11
	v_mul_f32_e32 v13, v12, v11
	v_fma_f32 v14, -v10, v13, v12
	v_fmac_f32_e32 v13, v14, v11
	v_fma_f32 v10, -v10, v13, v12
	v_div_fmas_f32 v10, v10, v11, v13
	v_div_fixup_f32 v42, v10, v9, v42
	ds_write_b32 v7, v42 offset:49176
	s_waitcnt vmcnt(8)
	v_mul_f32_e32 v10, 0xbfb8aa3b, v43
	v_exp_f32_e32 v10, v10
	s_nop 0
	v_add_f32_e32 v9, 1.0, v10
	v_div_scale_f32 v10, s[12:13], v9, v9, v43
	v_rcp_f32_e32 v11, v10
	v_div_scale_f32 v12, vcc, v43, v9, v43
	v_fma_f32 v13, -v10, v11, 1.0
	v_fmac_f32_e32 v11, v13, v11
	v_mul_f32_e32 v13, v12, v11
	v_fma_f32 v14, -v10, v13, v12
	v_fmac_f32_e32 v13, v14, v11
	v_fma_f32 v10, -v10, v13, v12
	v_div_fmas_f32 v10, v10, v11, v13
	v_div_fixup_f32 v43, v10, v9, v43
	ds_write_b32 v8, v43 offset:24
	s_waitcnt vmcnt(7)
; #define GAS __attribute__((address_space(1)))
; #define LAS __attribute__((address_space(3)))
; __device__ __forceinline__ void p0_modvec(const Params& p, LAS unsigned char* lds, int tid, int lane, int wave) {
;     ...
;     for (int i = tid; i < 9 * 2048; i += 512) { const float v = i < 8 * 2048 ? c[i] : cc[i - 8 * 2048]; svT[(i & 2047) * 12 + (i >> 11)] = v / (1.0f + __expf(-v)); }
;     float* MOD = (float*)(p.ws + WS_MOD);
;     const int ln = lane & 15, lk = lane >> 4;
;     const LAS float* svw = svT + (wave * 256 + lk) * 12 + min(ln, 11);
;     for (int u = blockIdx.x; u < 2 * (DMODW / UC); u += gridDim.x) {
;         __syncthreads();
;         const int l = u / (DMODW / UC), col0 = (u % (DMODW / UC)) * UC;
;         const GAS float* Wu = (const GAS float*)uniform_ptr(p.in[IN_WMOD] + (size_t)l * D * DMODW + col0 + (size_t)(wave * 256) * DMODW);
;         const unsigned loff = (unsigned)(lk * DMODW + ln);
	v_mul_f32_e32 v10, 0xbfb8aa3b, v44
	v_exp_f32_e32 v10, v10
	s_nop 0
	v_add_f32_e32 v9, 1.0, v10
	v_div_scale_f32 v10, s[12:13], v9, v9, v44
	v_rcp_f32_e32 v11, v10
	v_div_scale_f32 v12, vcc, v44, v9, v44
	v_fma_f32 v13, -v10, v11, 1.0
	v_fmac_f32_e32 v11, v13, v11
	v_mul_f32_e32 v13, v12, v11
	v_fma_f32 v14, -v10, v13, v12
	v_fmac_f32_e32 v13, v14, v11
	v_fma_f32 v10, -v10, v13, v12
	v_div_fmas_f32 v10, v10, v11, v13
	v_div_fixup_f32 v44, v10, v9, v44
	ds_write_b32 v7, v44 offset:28
	s_waitcnt vmcnt(6)
	v_mul_f32_e32 v10, 0xbfb8aa3b, v45
	v_exp_f32_e32 v10, v10
	s_nop 0
	v_add_f32_e32 v9, 1.0, v10
	v_div_scale_f32 v10, s[12:13], v9, v9, v45
	v_rcp_f32_e32 v11, v10
	v_div_scale_f32 v12, vcc, v45, v9, v45
	v_fma_f32 v13, -v10, v11, 1.0
	v_fmac_f32_e32 v11, v13, v11
	v_mul_f32_e32 v13, v12, v11
	v_fma_f32 v14, -v10, v13, v12
	v_fmac_f32_e32 v13, v14, v11
	v_fma_f32 v10, -v10, v13, v12
	v_div_fmas_f32 v10, v10, v11, v13
	v_div_fixup_f32 v45, v10, v9, v45
	ds_write_b32 v7, v45 offset:24604
	s_waitcnt vmcnt(5)
	v_mul_f32_e32 v10, 0xbfb8aa3b, v46
	v_exp_f32_e32 v10, v10
	s_nop 0
	v_add_f32_e32 v9, 1.0, v10
	v_div_scale_f32 v10, s[12:13], v9, v9, v46
	v_rcp_f32_e32 v11, v10
	v_div_scale_f32 v12, vcc, v46, v9, v46
	v_fma_f32 v13, -v10, v11, 1.0
	v_fmac_f32_e32 v11, v13, v11
	v_mul_f32_e32 v13, v12, v11
	v_fma_f32 v14, -v10, v13, v12
	v_fmac_f32_e32 v13, v14, v11
	v_fma_f32 v10, -v10, v13, v12
	v_div_fmas_f32 v10, v10, v11, v13
	v_div_fixup_f32 v46, v10, v9, v46
	ds_write_b32 v7, v46 offset:49180
	s_waitcnt vmcnt(4)
	v_mul_f32_e32 v10, 0xbfb8aa3b, v47
	v_exp_f32_e32 v10, v10
	s_nop 0
	v_add_f32_e32 v9, 1.0, v10
	v_div_scale_f32 v10, s[12:13], v9, v9, v47
	v_rcp_f32_e32 v11, v10
	v_div_scale_f32 v12, vcc, v47, v9, v47
	v_fma_f32 v13, -v10, v11, 1.0
	v_fmac_f32_e32 v11, v13, v11
	v_mul_f32_e32 v13, v12, v11
	v_fma_f32 v14, -v10, v13, v12
	v_fmac_f32_e32 v13, v14, v11
	v_fma_f32 v10, -v10, v13, v12
	v_div_fmas_f32 v10, v10, v11, v13
	v_div_fixup_f32 v47, v10, v9, v47
	ds_write_b32 v8, v47 offset:28
	s_waitcnt vmcnt(3)
	v_mul_f32_e32 v10, 0xbfb8aa3b, v48
	v_exp_f32_e32 v10, v10
	s_nop 0
	v_add_f32_e32 v9, 1.0, v10
	v_div_scale_f32 v10, s[12:13], v9, v9, v48
	v_rcp_f32_e32 v11, v10
	v_div_scale_f32 v12, vcc, v48, v9, v48
	v_fma_f32 v13, -v10, v11, 1.0
	v_fmac_f32_e32 v11, v13, v11
	v_mul_f32_e32 v13, v12, v11
	v_fma_f32 v14, -v10, v13, v12
	v_fmac_f32_e32 v13, v14, v11
	v_fma_f32 v10, -v10, v13, v12
	v_div_fmas_f32 v10, v10, v11, v13
	v_div_fixup_f32 v48, v10, v9, v48
	ds_write_b32 v7, v48 offset:32
	s_waitcnt vmcnt(2)
	v_mul_f32_e32 v10, 0xbfb8aa3b, v49
	v_exp_f32_e32 v10, v10
	s_nop 0
	v_add_f32_e32 v9, 1.0, v10
	v_div_scale_f32 v10, s[12:13], v9, v9, v49
	v_rcp_f32_e32 v11, v10
	v_div_scale_f32 v12, vcc, v49, v9, v49
	v_fma_f32 v13, -v10, v11, 1.0
	v_fmac_f32_e32 v11, v13, v11
	v_mul_f32_e32 v13, v12, v11
	v_fma_f32 v14, -v10, v13, v12
	v_fmac_f32_e32 v13, v14, v11
	v_fma_f32 v10, -v10, v13, v12
	v_div_fmas_f32 v10, v10, v11, v13
	v_div_fixup_f32 v49, v10, v9, v49
	ds_write_b32 v7, v49 offset:24608
	s_waitcnt vmcnt(1)
	v_mul_f32_e32 v10, 0xbfb8aa3b, v50
	v_exp_f32_e32 v10, v10
	s_nop 0
	v_add_f32_e32 v9, 1.0, v10
	v_div_scale_f32 v10, s[12:13], v9, v9, v50
	v_rcp_f32_e32 v11, v10
	v_div_scale_f32 v12, vcc, v50, v9, v50
	v_fma_f32 v13, -v10, v11, 1.0
	v_fmac_f32_e32 v11, v13, v11
	v_mul_f32_e32 v13, v12, v11
	v_fma_f32 v14, -v10, v13, v12
	v_fmac_f32_e32 v13, v14, v11
	v_fma_f32 v10, -v10, v13, v12
	v_div_fmas_f32 v10, v10, v11, v13
	v_div_fixup_f32 v50, v10, v9, v50
	ds_write_b32 v7, v50 offset:49184
	s_waitcnt vmcnt(0)
	v_mul_f32_e32 v10, 0xbfb8aa3b, v51
	v_exp_f32_e32 v10, v10
	s_nop 0
	v_add_f32_e32 v9, 1.0, v10
	v_div_scale_f32 v10, s[12:13], v9, v9, v51
	v_rcp_f32_e32 v11, v10
	v_div_scale_f32 v12, vcc, v51, v9, v51
	v_fma_f32 v13, -v10, v11, 1.0
	v_fmac_f32_e32 v11, v13, v11
	v_mul_f32_e32 v13, v12, v11
	v_fma_f32 v14, -v10, v13, v12
	v_fmac_f32_e32 v13, v14, v11
	v_fma_f32 v10, -v10, v13, v12
	v_div_fmas_f32 v10, v10, v11, v13
	v_div_fixup_f32 v51, v10, v9, v51
	ds_write_b32 v8, v51 offset:32
	s_nop 0
	s_nop 0
	s_nop 0
	s_nop 0
	s_nop 0
	s_nop 0
	s_nop 0
	s_nop 0
	s_nop 0
	s_nop 0
	s_nop 0
	s_nop 0
	s_nop 0
	s_nop 0
	s_nop 0
	s_or_b64 exec, exec, s[2:3]
	s_cmpk_gt_i32 s86, 0xff
	s_cbranch_scc1 .LBB0_91
	s_add_u32 s33, s88, 0x100000
	s_addc_u32 s62, s89, 0
	v_and_b32_e32 v3, 15, v0
	v_lshrrev_b32_e32 v4, 4, v1
	s_lshl_b32 s2, s10, 8
	v_or_b32_e32 v2, s2, v4
	v_min_u32_e32 v5, 11, v3
	v_mul_lo_u32 v2, v2, 48
	v_lshlrev_b32_e32 v5, 2, v5
	v_add3_u32 v40, 0, v2, v5
	s_mul_hi_u32 s65, s2, 0x12000
	v_lshlrev_b32_e32 v5, 2, v4
	s_mul_i32 s2, s10, 9
	v_mul_u32_u24_e32 v2, 0x4800, v4
	v_cmp_ne_u32_e32 vcc, 3, v4
	v_add_u32_e32 v4, s2, v5
	v_or_b32_e32 v6, 1, v5
	v_or_b32_e32 v7, 2, v5
	v_or_b32_e32 v5, 3, v5
	s_mul_i32 s63, s10, 0x1200000
	s_add_i32 s66, 0, 0x18000
	s_movk_i32 s3, 0x240
	v_cmp_gt_u32_e64 s[10:11], 9, v6
	v_add_u32_e32 v6, s2, v6
	v_cmp_gt_u32_e64 s[6:7], 9, v7
	v_add_u32_e32 v7, s2, v7
	v_cmp_gt_u32_e64 s[8:9], 9, v5
	v_add_u32_e32 v5, s2, v5
	v_or_b32_e32 v2, v2, v3
	v_lshl_add_u32 v3, v3, 2, s66
	v_mul_lo_u32 v4, v4, s3
	v_mul_lo_u32 v6, v6, s3
	v_mul_lo_u32 v7, v7, s3
	v_mul_lo_u32 v5, v5, s3
	s_mov_b32 s64, 0x12000
	v_mov_b32_e32 v39, 0
	v_lshlrev_b32_e32 v38, 2, v2
	v_add_u32_e32 v41, 0x400, v40
	v_add_u32_e32 v42, 0x600, v40
	v_add_u32_e32 v43, 0x800, v40
	v_add_u32_e32 v44, 0xc00, v40
	v_add_u32_e32 v45, 0x1000, v40
	v_add_u32_e32 v46, 0x1200, v40
	v_add_u32_e32 v47, 0x1400, v40
	v_add_u32_e32 v48, 0x1800, v40
	v_add_u32_e32 v49, 0x1c00, v40
	v_add_u32_e32 v50, 0x1e00, v40
	v_add_u32_e32 v51, 0x2000, v40
	v_add_u32_e32 v52, 0x2400, v40
	v_add_u32_e32 v53, 0x2800, v40
	v_add_u32_e32 v54, 0x2a00, v40
	v_add_u32_e32 v55, 0x2c00, v40
	v_add_u32_e32 v56, v3, v4
	v_add_u32_e32 v57, v3, v6
	v_add_u32_e32 v58, v3, v7
	v_add_u32_e32 v59, v3, v5
	s_mov_b32 s67, s86
	s_cmpk_lg_i32 s97, 0x100
	s_cbranch_scc1 .Lmv_keep
	s_and_b32 s67, s86, 7
	s_lshl_b32 s67, s67, 5
	s_lshr_b32 s2, s86, 3
	s_or_b32 s67, s67, s2
.Lmv_keep:
	s_nop 0
	s_nop 0
	s_nop 0
	s_nop 0
	s_nop 0
	s_nop 0
	s_nop 0
	s_nop 0
	s_nop 0
	s_nop 0
	s_mov_b64 s[2:3], 0xca8000
	s_mov_b64 s[14:15], 0xcf0000
	s_mov_b64 s[16:17], 0xd38000
	s_mov_b64 s[18:19], 0xd80000
	s_mov_b64 s[20:21], 0xdc8000
	s_mov_b64 s[22:23], 0xe10000
	s_mov_b64 s[24:25], 0xe58000
	s_mov_b64 s[26:27], 0xea0000
	s_mov_b64 s[28:29], 0xee8000
	s_mov_b64 s[30:31], 0xf30000
	s_mov_b64 s[34:35], 0xf78000
	s_mov_b64 s[36:37], 0xfc0000
	s_mov_b64 s[38:39], 0x1008000
	s_mov_b64 s[40:41], 0x1050000
	s_mov_b64 s[42:43], 0x1098000
	s_mov_b64 s[44:45], 0x10e0000
	s_mov_b64 s[46:47], 0x1128000
	s_mov_b64 s[48:49], 0x1170000
	s_mov_b64 s[50:51], 0x11b8000
	s_branch .LBB0_16
